# delta preprocess: the five raw-row ds_read_b128 issued at the top, ahead of the first read group (its temporaries renamed), to hide one LDS latency per chunk
# speedup vs baseline: 1.0054x; 1.0054x over previous
; __device__ __forceinline__ float bflo(unsigned u) { return __uint_as_float(u << 16); }
; __device__ __forceinline__ float bfhi(unsigned u) { return __uint_as_float(u & 0xffff0000u); }
; template <int N, int RS>
; __device__ __forceinline__ void convN(const bf16_t* rawb, const float (&w)[4][N], int tt, int off, float (&x)[N]) {
;     ...
;     if (N == 8) { const uint4 rv = *(const uint4*)(rawb + (tt + j) * RS + off); unpack8(rv, xv); }
;     else if (N == 4) { const uint2 rv = *(const uint2*)(rawb + (tt + j) * RS + off); xv[0] = bflo(rv.x); xv[1] = bfhi(rv.x); xv[2 % N] = bflo(rv.y); xv[3 % N] = bfhi(rv.y); }
;     else { const unsigned rv = *(const unsigned*)(rawb + (tt + j) * RS + off); xv[0] = bflo(rv); xv[1] = bfhi(rv); }
; #pragma unroll
;     for (int i = 0; i < N; ++i) x[i] += w[j][i] * xv[i];
; template <int MIX>
; __device__ __forceinline__ void scan_part(const Params& p, const int layer, const int smp, const int b0, const int bstep, const int bend, const int h, const int part, char* lds, const int tid) {
;     ...
;       if (valid) {
;         float xq[8], xk[8], xv[VN];
;         { float cwv[4][VN];
; #pragma unroll
;           for (int j = 0; j < 4; ++j)
; #pragma unroll
;             for (int i = 0; i < VN; ++i) cwv[j][i] = cwl[j * RS + 128 + sub * VN + i];
;           convN<VN, RS>(rawb, cwv, tt, 128 + sub * VN, xv); }
;         convN<8, RS>(rawb, cwq, tt, sub * 8, xq);
;         convN<8, RS>(rawb, cwk, tt, 64 + sub * 8, xk);
.Ld_top_done:
	s_and_saveexec_b64 s[50:51], s[42:43]
	s_cbranch_execz .LBB0_426
	v_add_u32_e32 v232, s23, v131
	v_lshlrev_b32_e32 v232, 2, v232
	ds_read_b32 v230, v232 offset:50880
	v_lshlrev_b32_e32 v231, 16, v133
	v_mul_f32_e32 v231, 0xbfb8aa3b, v231
	ds_read_b128 v[78:81], v151 offset:37376
	ds_read_b128 v[82:85], v151 offset:37504
	ds_read_b128 v[86:89], v151 offset:37664
	ds_read_b128 v[90:93], v151 offset:37952
	ds_read_b128 v[174:177], v151 offset:38240
	v_add_u32_e32 v2, v140, v138
	v_add_u32_e32 v0, 0x9200, v2
	v_add_u32_e32 v216, 0xbc00, v137
	v_exp_f32_e32 v231, v231
	ds_read2_b32 v[0:1], v0 offset0:64 offset1:136
	ds_read2_b64 v[216:219], v216 offset0:120 offset1:192
	v_add_u32_e32 v220, 0xc000, v137
	v_add_u32_e32 v2, 0x9400, v2
	v_add_f32_e32 v231, 1.0, v231
	ds_read2_b64 v[220:223], v220 offset0:136 offset1:208
	s_waitcnt lgkmcnt(2)
	v_lshlrev_b32_e32 v225, 16, v1
	v_lshlrev_b32_e32 v224, 16, v0
	v_rcp_f32_e32 v231, v231
	s_waitcnt lgkmcnt(1)
	v_mov_b32_e32 v226, v216
	v_mov_b32_e32 v227, v218
	v_pk_mul_f32 v[224:225], v[226:227], v[224:225]
	v_and_b32_e32 v1, 0xffff0000, v1
	v_add_f32_e32 v216, 0, v224
	v_add_f32_e32 v226, v216, v225
	ds_read2_b32 v[224:225], v2 offset0:80 offset1:152
	v_and_b32_e32 v0, 0xffff0000, v0
	v_mov_b32_e32 v218, v217
	v_pk_mul_f32 v[0:1], v[218:219], v[0:1]
	s_waitcnt lgkmcnt(1)
	v_mov_b32_e32 v216, v220
	v_add_f32_e32 v0, 0, v0
	v_add_f32_e32 v2, v0, v1
	s_waitcnt lgkmcnt(0)
	v_lshlrev_b32_e32 v1, 16, v225
	v_lshlrev_b32_e32 v0, 16, v224
	v_mov_b32_e32 v217, v222
	v_pk_mul_f32 v[0:1], v[216:217], v[0:1]
	v_and_b32_e32 v217, 0xffff0000, v225
	v_and_b32_e32 v216, 0xffff0000, v224
	v_mov_b32_e32 v222, v221
	v_add_f32_e32 v0, v226, v0
	v_pk_mul_f32 v[216:217], v[222:223], v[216:217]
	v_add_f32_e32 v0, v0, v1
	v_add_f32_e32 v1, v2, v216
	v_add_f32_e32 v1, v1, v217
	v_mul_f32_e32 v2, 0xbfb8aa3b, v0
	v_exp_f32_e32 v2, v2
	v_mul_f32_e32 v76, 0xbfb8aa3b, v1
	v_exp_f32_e32 v77, v76
	s_waitcnt lgkmcnt(4)
	v_lshlrev_b32_e32 v154, 16, v80
	v_and_b32_e32 v155, 0xffff0000, v80
	v_lshlrev_b32_e32 v94, 16, v78
	v_and_b32_e32 v95, 0xffff0000, v78
	v_lshlrev_b32_e32 v106, 16, v79
	v_and_b32_e32 v107, 0xffff0000, v79
	v_lshlrev_b32_e32 v178, 16, v81
	v_and_b32_e32 v179, 0xffff0000, v81
	ds_read_b128 v[78:81], v151 offset:37792
	s_waitcnt lgkmcnt(3)
	v_lshlrev_b32_e32 v180, 16, v86
	v_and_b32_e32 v181, 0xffff0000, v86
	v_lshlrev_b32_e32 v182, 16, v87
	v_and_b32_e32 v183, 0xffff0000, v87
	v_lshlrev_b32_e32 v184, 16, v88
	v_and_b32_e32 v185, 0xffff0000, v88
	v_lshlrev_b32_e32 v186, 16, v89
	v_and_b32_e32 v187, 0xffff0000, v89
	ds_read_b128 v[86:89], v151 offset:38080
	s_waitcnt lgkmcnt(3)
	v_lshlrev_b32_e32 v188, 16, v90
	v_and_b32_e32 v189, 0xffff0000, v90
	v_lshlrev_b32_e32 v190, 16, v91
	v_and_b32_e32 v191, 0xffff0000, v91
	v_lshlrev_b32_e32 v192, 16, v92
	v_and_b32_e32 v193, 0xffff0000, v92
	v_lshlrev_b32_e32 v194, 16, v93
	v_and_b32_e32 v195, 0xffff0000, v93
	ds_read_b128 v[90:93], v151 offset:38368
	s_waitcnt vmcnt(2)
	v_pk_fma_f32 v[154:155], v[4:5], v[154:155], 0 op_sel_hi:[1,1,0]
	v_add_f32_e32 v2, 1.0, v2
	s_waitcnt vmcnt(2)
	v_pk_fma_f32 v[154:155], v[12:13], v[184:185], v[154:155]
	s_waitcnt lgkmcnt(3)
	v_lshlrev_b32_e32 v198, 16, v176
	v_and_b32_e32 v199, 0xffff0000, v176
	s_waitcnt vmcnt(2)
	v_pk_fma_f32 v[154:155], v[20:21], v[192:193], v[154:155]
	v_rcp_f32_e32 v76, v2
	v_add_f32_e32 v2, 1.0, v77
	s_waitcnt vmcnt(2)
	v_pk_fma_f32 v[154:155], v[28:29], v[198:199], v[154:155]
	v_rcp_f32_e32 v77, v2
	v_mul_f32_e32 v2, 0xbfb8aa3b, v154
	v_lshlrev_b32_e32 v202, 16, v84
	v_and_b32_e32 v203, 0xffff0000, v84
	s_waitcnt lgkmcnt(0)
	v_lshlrev_b32_e32 v214, 16, v92
	v_and_b32_e32 v215, 0xffff0000, v92
	v_exp_f32_e32 v2, v2
	v_mul_f32_e32 v92, 0xbfb8aa3b, v155
	v_lshlrev_b32_e32 v206, 16, v80
	v_and_b32_e32 v207, 0xffff0000, v80
	v_exp_f32_e32 v158, v92
	s_waitcnt vmcnt(2)
	v_pk_fma_f32 v[192:193], v[36:37], v[202:203], 0 op_sel_hi:[1,1,0]
	v_lshlrev_b32_e32 v210, 16, v88
	v_and_b32_e32 v211, 0xffff0000, v88
	s_waitcnt vmcnt(2)
	v_pk_fma_f32 v[192:193], v[44:45], v[206:207], v[192:193]
	v_add_f32_e32 v2, 1.0, v2
	s_waitcnt vmcnt(2)
	v_pk_fma_f32 v[192:193], v[52:53], v[210:211], v[192:193]
	v_rcp_f32_e32 v184, v2
	s_waitcnt vmcnt(2)
; __device__ __forceinline__ float bflo(unsigned u) { return __uint_as_float(u << 16); }
; __device__ __forceinline__ float bfhi(unsigned u) { return __uint_as_float(u & 0xffff0000u); }
; __device__ __forceinline__ float siluf_(float x) { return x * __builtin_amdgcn_rcpf(1.0f + __expf(-x)); }
; template <int N, int RS>
; __device__ __forceinline__ void convN(const bf16_t* rawb, const float (&w)[4][N], int tt, int off, float (&x)[N]) {
; #pragma unroll
;   for (int i = 0; i < N; ++i) x[i] = 0.f;
; #pragma unroll
;   for (int j = 0; j < 4; ++j) {
;     float xv[N];
;     if (N == 8) { const uint4 rv = *(const uint4*)(rawb + (tt + j) * RS + off); unpack8(rv, xv); }
;     else if (N == 4) { const uint2 rv = *(const uint2*)(rawb + (tt + j) * RS + off); xv[0] = bflo(rv.x); xv[1] = bfhi(rv.x); xv[2 % N] = bflo(rv.y); xv[3 % N] = bfhi(rv.y); }
;     else { const unsigned rv = *(const unsigned*)(rawb + (tt + j) * RS + off); xv[0] = bflo(rv); xv[1] = bfhi(rv); }
; #pragma unroll
;     for (int i = 0; i < N; ++i) x[i] += w[j][i] * xv[i];
;   }
;   if (N == 2) {
; #pragma unroll
;     for (int i = 0; i < N; ++i) asm volatile("" : "+v"(x[i]));
;   }
; #pragma unroll
;   for (int i = 0; i < N; ++i) x[i] = siluf_(x[i]);
; template <int MIX>
; __device__ __forceinline__ void scan_part(const Params& p, const int layer, const int smp, const int b0, const int bstep, const int bend, const int h, const int part, char* lds, const int tid) {
;     ...
;         convN<8, RS>(rawb, cwq, tt, sub * 8, xq);
;         convN<8, RS>(rawb, cwk, tt, 64 + sub * 8, xk);
	v_pk_fma_f32 v[192:193], v[60:61], v[214:215], v[192:193]
	v_add_f32_e32 v2, 1.0, v158
	v_mul_f32_e32 v158, 0xbfb8aa3b, v192
	v_exp_f32_e32 v158, v158
	v_mul_f32_e32 v159, 0xbfb8aa3b, v193
	v_exp_f32_e32 v159, v159
	v_pk_fma_f32 v[178:179], v[6:7], v[178:179], 0 op_sel_hi:[1,1,0]
	v_lshlrev_b32_e32 v176, 16, v177
	v_pk_fma_f32 v[178:179], v[14:15], v[186:187], v[178:179]
	v_and_b32_e32 v177, 0xffff0000, v177
	v_rcp_f32_e32 v185, v2
	v_add_f32_e32 v2, 1.0, v158
	v_pk_fma_f32 v[178:179], v[22:23], v[194:195], v[178:179]
	v_rcp_f32_e32 v198, v2
	v_add_f32_e32 v2, 1.0, v159
	v_pk_fma_f32 v[176:177], v[30:31], v[176:177], v[178:179]
	v_rcp_f32_e32 v199, v2
	v_mul_f32_e32 v2, 0xbfb8aa3b, v176
	v_exp_f32_e32 v2, v2
	v_mul_f32_e32 v158, 0xbfb8aa3b, v177
	v_exp_f32_e32 v158, v158
	v_pk_fma_f32 v[94:95], v[8:9], v[94:95], 0 op_sel_hi:[1,1,0]
	v_lshlrev_b32_e32 v196, 16, v174
	v_pk_fma_f32 v[94:95], v[16:17], v[180:181], v[94:95]
	v_and_b32_e32 v197, 0xffff0000, v174
	v_add_f32_e32 v2, 1.0, v2
	v_pk_fma_f32 v[94:95], v[24:25], v[188:189], v[94:95]
	v_rcp_f32_e32 v186, v2
	v_add_f32_e32 v2, 1.0, v158
	v_pk_fma_f32 v[94:95], v[32:33], v[196:197], v[94:95]
	v_rcp_f32_e32 v187, v2
	v_mul_f32_e32 v2, 0xbfb8aa3b, v94
	v_exp_f32_e32 v2, v2
	v_mul_f32_e32 v158, 0xbfb8aa3b, v95
	v_exp_f32_e32 v158, v158
	v_pk_fma_f32 v[106:107], v[10:11], v[106:107], 0 op_sel_hi:[1,1,0]
	v_lshlrev_b32_e32 v174, 16, v175
	v_pk_fma_f32 v[106:107], v[18:19], v[182:183], v[106:107]
	v_and_b32_e32 v175, 0xffff0000, v175
	v_pk_fma_f32 v[106:107], v[26:27], v[190:191], v[106:107]
	v_add_f32_e32 v2, 1.0, v2
	v_pk_fma_f32 v[106:107], v[34:35], v[174:175], v[106:107]
	v_rcp_f32_e32 v180, v2
	v_add_f32_e32 v2, 1.0, v158
	v_mul_f32_e32 v158, 0xbfb8aa3b, v106
	v_exp_f32_e32 v158, v158
	v_mul_f32_e32 v159, 0xbfb8aa3b, v107
	v_lshlrev_b32_e32 v84, 16, v85
	v_and_b32_e32 v85, 0xffff0000, v85
	v_exp_f32_e32 v159, v159
	v_lshlrev_b32_e32 v80, 16, v81
	v_and_b32_e32 v81, 0xffff0000, v81
	v_pk_fma_f32 v[84:85], v[38:39], v[84:85], 0 op_sel_hi:[1,1,0]
	v_lshlrev_b32_e32 v88, 16, v89
	v_and_b32_e32 v89, 0xffff0000, v89
	v_pk_fma_f32 v[80:81], v[46:47], v[80:81], v[84:85]
	v_lshlrev_b32_e32 v92, 16, v93
	v_and_b32_e32 v93, 0xffff0000, v93
	v_rcp_f32_e32 v181, v2
	v_add_f32_e32 v2, 1.0, v158
	v_pk_fma_f32 v[80:81], v[54:55], v[88:89], v[80:81]
	v_rcp_f32_e32 v174, v2
	v_add_f32_e32 v2, 1.0, v159
	v_pk_fma_f32 v[80:81], v[62:63], v[92:93], v[80:81]
	v_rcp_f32_e32 v175, v2
	v_mul_f32_e32 v2, 0xbfb8aa3b, v80
	v_exp_f32_e32 v2, v2
	v_mul_f32_e32 v84, 0xbfb8aa3b, v81
	v_exp_f32_e32 v89, v84
	v_lshlrev_b32_e32 v200, 16, v82
	v_and_b32_e32 v201, 0xffff0000, v82
	v_lshlrev_b32_e32 v204, 16, v78
	v_and_b32_e32 v205, 0xffff0000, v78
	v_add_f32_e32 v2, 1.0, v2
	v_pk_fma_f32 v[92:93], v[40:41], v[200:201], 0 op_sel_hi:[1,1,0]
	v_lshlrev_b32_e32 v82, 16, v83
	v_and_b32_e32 v83, 0xffff0000, v83
	v_lshlrev_b32_e32 v208, 16, v86
	v_and_b32_e32 v209, 0xffff0000, v86
	v_rcp_f32_e32 v88, v2
	v_add_f32_e32 v2, 1.0, v89
	v_pk_fma_f32 v[92:93], v[48:49], v[204:205], v[92:93]
	v_lshlrev_b32_e32 v78, 16, v79
	v_and_b32_e32 v79, 0xffff0000, v79
	v_lshlrev_b32_e32 v212, 16, v90
	v_and_b32_e32 v213, 0xffff0000, v90
	v_rcp_f32_e32 v89, v2
	v_pk_fma_f32 v[92:93], v[56:57], v[208:209], v[92:93]
	v_pk_fma_f32 v[82:83], v[42:43], v[82:83], 0 op_sel_hi:[1,1,0]
	v_lshlrev_b32_e32 v86, 16, v87
	v_and_b32_e32 v87, 0xffff0000, v87
	s_waitcnt vmcnt(2)
; __device__ __forceinline__ float bflo(unsigned u) { return __uint_as_float(u << 16); }
; __device__ __forceinline__ float sigmoidf_(float x) { return __builtin_amdgcn_rcpf(1.0f + __expf(-x)); }
; __device__ __forceinline__ float softplusf_(float x) { return fmaxf(x, 0.f) + __logf(1.0f + __expf(-fabsf(x))); }
; __device__ __forceinline__ float red8d(float x) { x += dpp_x1(x); x += dpp_x2(x); x += dpp_hm(x); return x; }
; template <int MIX>
; __device__ __forceinline__ void scan_part(const Params& p, const int layer, const int smp, const int b0, const int bstep, const int bend, const int h, const int part, char* lds, const int tid) {
;     ...
; #pragma unroll
;         for (int i = 0; i < VN; ++i) dst[192 + sub * VN + i] = xv[i];
;         float ssq = 0.f, ssk = 0.f;
; #pragma unroll
;         for (int i = 0; i < 8; ++i) { ssq += xq[i] * xq[i]; ssk += xk[i] * xk[i]; }
;         ssq = red8d(ssq); ssk = red8d(ssk);
;         const float rq = rsqrtf(ssq + 1e-6f) * 0.125f, rk = rsqrtf(ssk + 1e-6f);
;         float qk = 0.f;
; #pragma unroll
;         for (int i = 0; i < 8; ++i) { xq[i] *= rq; xk[i] *= rk; qk += xq[i] * xk[i]; }
;         qk = red8d(qk);
;         *(f32x4*)(dst + sub * 8) = (f32x4){xq[0], xq[1], xq[2], xq[3]}; *(f32x4*)(dst + sub * 8 + 4) = (f32x4){xq[4], xq[5], xq[6], xq[7]};
;         *(f32x4*)(dst + 64 + sub * 8) = (f32x4){xk[0], xk[1], xk[2], xk[3]}; *(f32x4*)(dst + 64 + sub * 8 + 4) = (f32x4){xk[4], xk[5], xk[6], xk[7]};
;         if (sub == 0) {
;           const float be = sigmoidf_(bflo(ex0)), al = bflo(ex1);
;           const float a = __expf(-Aexp * softplusf_(al + dtb));
;           *(f32x4*)(scal + tt * 4) = (f32x4){a, be, qk, 0.f};
;         }
	v_pk_fma_f32 v[92:93], v[64:65], v[212:213], v[92:93]
	v_pk_fma_f32 v[78:79], v[50:51], v[78:79], v[82:83]
	v_lshlrev_b32_e32 v90, 16, v91
	v_and_b32_e32 v91, 0xffff0000, v91
	v_mul_f32_e32 v2, 0xbfb8aa3b, v92
	v_pk_fma_f32 v[78:79], v[58:59], v[86:87], v[78:79]
	v_exp_f32_e32 v2, v2
	v_mul_f32_e32 v158, 0xbfb8aa3b, v93
	v_pk_fma_f32 v[78:79], v[66:67], v[90:91], v[78:79]
	v_pk_mul_f32 v[106:107], v[106:107], v[174:175]
	v_exp_f32_e32 v158, v158
	v_pk_mul_f32 v[174:175], v[80:81], v[88:89]
	v_mul_f32_e32 v81, 0xbfb8aa3b, v78
	v_exp_f32_e32 v82, v81
	v_mul_f32_e32 v81, 0xbfb8aa3b, v79
	v_exp_f32_e32 v83, v81
	v_add_f32_e32 v2, 1.0, v2
	v_rcp_f32_e32 v80, v2
	v_add_f32_e32 v2, 1.0, v158
	v_rcp_f32_e32 v81, v2
	v_add_f32_e32 v2, 1.0, v82
	v_rcp_f32_e32 v82, v2
	v_add_f32_e32 v2, 1.0, v83
	v_rcp_f32_e32 v83, v2
	v_pk_mul_f32 v[94:95], v[94:95], v[180:181]
	v_pk_mul_f32 v[88:89], v[92:93], v[80:81]
	v_pk_mul_f32 v[180:181], v[94:95], v[94:95]
	v_pk_mul_f32 v[80:81], v[88:89], v[88:89]
	v_pk_mul_f32 v[90:91], v[78:79], v[82:83]
	v_pk_mul_f32 v[84:85], v[106:107], v[106:107]
	v_pk_mul_f32 v[78:79], v[90:91], v[90:91]
	v_mov_b32_e32 v82, v80
	v_mov_b32_e32 v83, v180
	v_mov_b32_e32 v180, v81
	v_pk_mul_f32 v[154:155], v[154:155], v[184:185]
	v_pk_mul_f32 v[192:193], v[192:193], v[198:199]
	v_pk_add_f32 v[80:81], v[82:83], v[180:181]
	v_mov_b32_e32 v82, v78
	v_mov_b32_e32 v83, v84
	v_pk_mul_f32 v[184:185], v[154:155], v[154:155]
	v_pk_mul_f32 v[178:179], v[192:193], v[192:193]
	v_pk_add_f32 v[80:81], v[80:81], v[82:83]
	v_mov_b32_e32 v84, v79
	v_pk_mul_f32 v[176:177], v[176:177], v[186:187]
	v_pk_add_f32 v[78:79], v[84:85], v[80:81]
	v_mov_b32_e32 v80, v178
	v_mov_b32_e32 v81, v184
	v_pk_mul_f32 v[182:183], v[176:177], v[176:177]
	v_pk_mul_f32 v[86:87], v[174:175], v[174:175]
	v_pk_add_f32 v[78:79], v[80:81], v[78:79]
	v_mov_b32_e32 v184, v179
	v_pk_add_f32 v[78:79], v[184:185], v[78:79]
	v_mov_b32_e32 v80, v86
	v_mov_b32_e32 v81, v182
	v_pk_add_f32 v[78:79], v[80:81], v[78:79]
	v_mov_b32_e32 v182, v87
	v_pk_add_f32 v[78:79], v[182:183], v[78:79]
	s_mov_b32 s44, 0x358637bd
	v_pk_mul_f32 v[0:1], v[0:1], v[76:77]
	v_mov_b32_dpp v81, v79 quad_perm:[1,0,3,2] row_mask:0xf bank_mask:0xf bound_ctrl:1
	v_mov_b32_dpp v80, v78 quad_perm:[1,0,3,2] row_mask:0xf bank_mask:0xf bound_ctrl:1
	v_pk_add_f32 v[78:79], v[78:79], v[80:81]
	ds_write_b64 v141, v[0:1] offset:768
	s_nop 0
	v_mov_b32_dpp v81, v79 quad_perm:[2,3,0,1] row_mask:0xf bank_mask:0xf bound_ctrl:1
	v_mov_b32_dpp v80, v78 quad_perm:[2,3,0,1] row_mask:0xf bank_mask:0xf bound_ctrl:1
	v_pk_add_f32 v[78:79], v[78:79], v[80:81]
	s_nop 1
	v_mov_b32_dpp v81, v79 row_half_mirror row_mask:0xf bank_mask:0xf bound_ctrl:1
	v_mov_b32_dpp v80, v78 row_half_mirror row_mask:0xf bank_mask:0xf bound_ctrl:1
	v_pk_add_f32 v[78:79], v[78:79], v[80:81]
	s_nop 0
	v_pk_add_f32 v[78:79], v[78:79], s[44:45] op_sel_hi:[1,0]
	s_nop 0
	v_mul_f32_e32 v2, 0x4b800000, v79
	v_cmp_gt_f32_e32 vcc, s92, v79
	s_nop 1
	v_cndmask_b32_e32 v2, v79, v2, vcc
	v_rsq_f32_e32 v2, v2
	s_nop 0
	v_mul_f32_e32 v0, 0x45800000, v2
	v_cndmask_b32_e32 v0, v2, v0, vcc
	v_mul_f32_e32 v0, 0x3e000000, v0
	v_pk_mul_f32 v[76:77], v[94:95], v[0:1] op_sel_hi:[1,0]
	v_mul_f32_e32 v1, 0x4b800000, v78
	v_cmp_gt_f32_e32 vcc, s92, v78
	s_nop 1
	v_cndmask_b32_e32 v1, v78, v1, vcc
	v_rsq_f32_e32 v1, v1
	s_nop 0
	v_pk_mul_f32 v[78:79], v[106:107], v[0:1] op_sel_hi:[1,0]
	v_pk_mul_f32 v[80:81], v[154:155], v[0:1] op_sel_hi:[1,0]
	v_pk_mul_f32 v[82:83], v[176:177], v[0:1] op_sel_hi:[1,0]
	v_mul_f32_e32 v0, 0x45800000, v1
	v_cndmask_b32_e32 v0, v1, v0, vcc
	v_pk_mul_f32 v[84:85], v[88:89], v[0:1] op_sel_hi:[1,0]
	s_nop 0
	v_pk_mul_f32 v[86:87], v[90:91], v[0:1] op_sel_hi:[1,0]
	s_nop 0
	v_pk_mul_f32 v[88:89], v[192:193], v[0:1] op_sel_hi:[1,0]
	s_nop 0
	v_pk_mul_f32 v[90:91], v[174:175], v[0:1] op_sel_hi:[1,0]
	ds_write_b128 v152, v[76:79]
	ds_write_b128 v152, v[80:83] offset:16
	ds_write_b128 v152, v[84:87] offset:256
	ds_write_b128 v152, v[88:91] offset:272
	s_and_b64 exec, exec, s[38:39]
	s_cbranch_execz .LBB0_426
	v_mov_b32_e32 v2, 0
	s_waitcnt lgkmcnt(5)
	v_mov_b32_e32 v0, v230
	v_mov_b32_e32 v1, v231
	ds_write_b128 v142, v[0:3] offset:36864
